# v022 + z-gate loads requested right after the first attention prologue barrier of each unit, consumed in the unit epilogue
# speedup vs baseline: 1.0089x; 1.0062x over previous
; template <bool HAS_POST, class MaskF>
; __device__ __forceinline__ void attn_run(LAS unsigned char* lds, const bf16* Kg, const bf16* Vg, int pitch, int t0, int t1,
;                                          const bf16x8 (&qr)[4], f32x16& o0, f32x16& o1, f32x16& o2, MaskF& mf, const int wv) {
;     ...
;     if (t0 >= t1) return;
;     const int lrow = tid >> 3, lch = tid & 7;
;     const unsigned kwoff = lrow * 144 + lch * 16;
;     const unsigned vwoff = ATT_V0 + lrow * 128 + (((lch >> 1) ^ (((lrow >> 1) & 1) << 1)) * 32) + (lch & 1) * 16;
;     const bf16* kp = Kg + (size_t)(64 * t0 + lrow) * pitch + lch * 8;
;     const bf16* vp = Vg + (size_t)(64 * t0 + lrow) * pitch + lch * 8;
;     const size_t tstride = (size_t)64 * pitch;
;     const v4u z4 = (v4u){0u, 0u, 0u, 0u};
;     v4u kreg0 = *(const v4u*)kp, kreg1 = z4, vreg0 = *(const v4u*)vp, vreg1 = z4;
;     if (t0 + 1 < t1) { kreg1 = *(const v4u*)(kp + tstride); vreg1 = *(const v4u*)(vp + tstride); }
; __device__ __forceinline__ void nsa_unit(const int wv, LAS unsigned char* lds, int b, int g, int c, const bf16* Y, const bf16* KCMP, const bf16* VCMP, const float* gates, bf16* OG) {
;     const int tid_ = fresh_tid(wv);
;     const int tid = tid_, lane = tid & 63, r32 = lane & 31, hi = lane >> 5, wid = tid >> 6;
;     const int hr = wid >> 1, tq = 32 * (wid & 1) + r32, tabs = 64 * c + tq, hh = 4 * g + hr;
;     LAS float* imph = (LAS float*)(lds + LDS_IMP);
;     LAS unsigned long long* selm = (LAS unsigned long long*)(lds + LDS_SEL);
;     for (int i = tid; i < 4 * 64 * 65; i += NTHREADS) imph[i] = 0.f;
;     __syncthreads();
;     const size_t row = (size_t)b * T + tabs;
;     bf16x8 qr[4]; load_q(Y + row * NSA_LDY + hh * 64, hi, qr);
;     const float* gp = gates + row * 48 + hh * 3; const float g0 = gp[0], g1 = gp[1], g2 = gp[2];
;     f32x16 acc0 = zero16(), acc1 = zero16();
;     LAS float* invl = (LAS float*)(lds + LDS_SEL + 512);
;     {
;         int ncnt = 4 * c + 3; if (ncnt > 255) ncnt = 255; const int nct = (ncnt + 63) >> 6;
;         CmpMask mf; mf.tabs = tabs; mf.hi = hi; mf.imp = imph + (hr * 64 + tq) * 65;
;         const bf16* Kg = KCMP + (size_t)(b * 4 + g) * 256 * 64; const bf16* Vg = VCMP + (size_t)(b * 4 + g) * 256 * 64;
;         f32x16 o0 = zero16(), o1 = zero16(), o2 = zero16();
;         attn_run<true>(lds, Kg, Vg, 64, 0, nct, qr, o0, o1, o2, mf, wv);
.LBB0_843:
	s_or_b64 exec, exec, s[4:5]
	v_lshrrev_b32_e32 v0, 1, v160
	v_and_b32_e32 v2, 31, v33
	v_and_b32_e32 v3, 32, v0
	v_or_b32_e32 v158, v3, v2
	v_readlane_b32 s0, v254, 57
	v_ashrrev_i32_e32 v8, 7, v160
	v_bfe_u32 v159, v33, 5, 1
	v_or_b32_e32 v152, s0, v158
	s_lshl_b32 s0, s19, 2
	v_writelane_b32 v254, s0, 21
	v_add_u32_e32 v9, s0, v8
	v_readlane_b32 s0, v254, 9
	v_ashrrev_i32_e32 v153, 31, v152
	v_readlane_b32 s1, v254, 10
	v_lshlrev_b32_e32 v6, 6, v9
	v_ashrrev_i32_e32 v7, 31, v6
	v_lshl_add_u64 v[0:1], s[0:1], 0, v[152:153]
	v_readlane_b32 s0, v254, 27
	v_readlane_b32 s1, v254, 28
	v_lshlrev_b32_e32 v114, 4, v159
	s_waitcnt lgkmcnt(0)
	v_mov_b64_e32 v[4:5], s[0:1]
	v_mad_u64_u32 v[4:5], s[0:1], v0, s84, v[4:5]
	v_mad_i32_i24 v5, v1, s84, v5
	v_lshl_add_u64 v[4:5], v[6:7], 1, v[4:5]
	v_readlane_b32 s0, v254, 35
	v_lshl_add_u64 v[4:5], v[4:5], 0, v[114:115]
	v_readlane_b32 s1, v254, 36
	s_barrier
	global_load_dwordx4 v[116:119], v[4:5], off
	global_load_dwordx4 v[120:123], v[4:5], off offset:32
	global_load_dwordx4 v[124:127], v[4:5], off offset:64
	global_load_dwordx4 v[128:131], v[4:5], off offset:96
	v_add_co_u32_e32 v210, vcc, 0x1000, v4
	s_nop 1
	v_addc_co_u32_e32 v211, vcc, 0, v5, vcc
	v_mov_b64_e32 v[4:5], s[0:1]
	s_movk_i32 s4, 0xc0
	v_mad_u64_u32 v[4:5], s[0:1], v0, s4, v[4:5]
	v_lshl_add_u32 v0, v9, 1, v9
	v_mad_i32_i24 v5, v1, s4, v5
	v_ashrrev_i32_e32 v1, 31, v0
	v_lshl_add_u64 v[0:1], v[0:1], 2, v[4:5]
	global_load_dwordx3 v[182:184], v[0:1], off
	v_mov_b32_e32 v0, v115
	v_readlane_b32 s0, v254, 37
	v_mov_b32_e32 v0, v115
	v_readlane_b32 s1, v254, 38
	v_lshlrev_b32_e32 v153, 6, v8
	v_mov_b32_e32 v161, v115
	v_mov_b32_e32 v162, v115
	v_mov_b32_e32 v32, v115
	s_mov_b64 s[4:5], -1
	s_and_b64 vcc, exec, s[0:1]
	v_mbcnt_lo_u32_b32 v4, -1, 0
	v_mbcnt_hi_u32_b32 v4, -1, v4
	s_cbranch_vccz .LBB0_878
	s_lshl_b32 s0, s19, 14
	v_readlane_b32 s1, v254, 39
	s_add_i32 s0, s0, s1
	s_lshl_b32 s4, s0, 1
	v_readlane_b32 s0, v254, 33
	v_add_u32_e32 v5, s83, v4
	s_add_u32 s0, s0, s4
	v_readlane_b32 s1, v254, 34
	s_addc_u32 s1, s1, 0
	v_readlane_b32 s5, v254, 31
	v_ashrrev_i32_e32 v0, 3, v5
	s_add_u32 s4, s5, s4
	v_readlane_b32 s5, v254, 32
	v_ashrrev_i32_e32 v1, 31, v0
	s_addc_u32 s5, s5, 0
	v_and_b32_e32 v6, 7, v4
	v_lshlrev_b64 v[8:9], 7, v[0:1]
	v_lshl_add_u64 v[10:11], s[4:5], 0, v[8:9]
	v_lshlrev_b32_e32 v114, 4, v6
	v_lshl_add_u64 v[154:155], v[10:11], 0, v[114:115]
	v_lshl_add_u64 v[8:9], s[0:1], 0, v[8:9]
	v_lshl_add_u64 v[156:157], v[8:9], 0, v[114:115]
	global_load_dwordx4 v[82:85], v[154:155], off
	global_load_dwordx4 v[86:89], v[156:157], off
	v_readlane_b32 s0, v254, 40
	v_readlane_b32 s1, v254, 41
	s_andn2_b64 vcc, exec, s[0:1]
	s_cbranch_vccnz .LBB0_846
	v_add_co_u32_e32 v8, vcc, 0x2000, v154
	s_nop 1
	v_addc_co_u32_e32 v9, vcc, 0, v155, vcc
	v_add_co_u32_e32 v10, vcc, 0x2000, v156
	s_nop 1
	v_addc_co_u32_e32 v11, vcc, 0, v157, vcc
	global_load_dwordx4 v[90:93], v[8:9], off
	global_load_dwordx4 v[94:97], v[10:11], off
	s_branch .LBB0_847

; #define LAS __attribute__((address_space(3)))
; template <bool HAS_POST, class MaskF>
; __device__ __forceinline__ void attn_run(LAS unsigned char* lds, const bf16* Kg, const bf16* Vg, int pitch, int t0, int t1,
;                                          const bf16x8 (&qr)[4], f32x16& o0, f32x16& o1, f32x16& o2, MaskF& mf, const int wv) {
;     ...
;     const unsigned kwoff = lrow * 144 + lch * 16;
;     const unsigned vwoff = ATT_V0 + lrow * 128 + (((lch >> 1) ^ (((lrow >> 1) & 1) << 1)) * 32) + (lch & 1) * 16;
;     const bf16* kp = Kg + (size_t)(64 * t0 + lrow) * pitch + lch * 8;
;     const bf16* vp = Vg + (size_t)(64 * t0 + lrow) * pitch + lch * 8;
;     const size_t tstride = (size_t)64 * pitch;
;     const v4u z4 = (v4u){0u, 0u, 0u, 0u};
;     v4u kreg0 = *(const v4u*)kp, kreg1 = z4, vreg0 = *(const v4u*)vp, vreg1 = z4;
;     if (t0 + 1 < t1) { kreg1 = *(const v4u*)(kp + tstride); vreg1 = *(const v4u*)(vp + tstride); }
;     *(LAS v4u*)(lds + kwoff) = kreg0; *(LAS v4u*)(lds + KBUF + kwoff) = kreg1;
;     *(LAS v4u*)(lds + vwoff) = vreg0; *(LAS v4u*)(lds + VBUF + vwoff) = vreg1;
;     __syncthreads();
.LBB0_847:
	v_lshrrev_b32_e32 v6, 1, v6
	v_lshrrev_b32_e32 v7, 3, v4
	s_movk_i32 s0, 0x90
	v_bitop3_b32 v6, v6, v7, 2 bitop3:0x78
	v_lshlrev_b32_e32 v7, 4, v4
	v_mul_lo_u32 v1, v0, s0
	v_lshlrev_b32_e32 v0, 7, v0
	v_lshlrev_b32_e32 v6, 5, v6
	v_and_b32_e32 v7, 16, v7
	v_readlane_b32 s0, v253, 63
	v_or3_b32 v0, v0, v6, v7
	v_readlane_b32 s1, v254, 0
	v_add3_u32 v114, v1, v114, 0
	v_add_u32_e32 v163, 0, v0
	s_andn2_b64 vcc, exec, s[0:1]
	s_waitcnt vmcnt(0)
	ds_write_b128 v114, v[82:85]
	ds_write_b128 v114, v[90:93] offset:9216
	s_waitcnt vmcnt(0)
	ds_write_b128 v163, v[86:89] offset:36864
	ds_write_b128 v163, v[94:97] offset:45056
	s_waitcnt lgkmcnt(0)
	s_barrier
	global_load_dwordx4 v[212:215], v[210:211], off
	global_load_dwordx4 v[216:219], v[210:211], off offset:32
	global_load_dwordx4 v[220:223], v[210:211], off offset:64
	global_load_dwordx4 v[224:227], v[210:211], off offset:96
	s_cbranch_vccnz .LBB0_849
	s_setprio 1

; template <bool HAS_POST, class MaskF>
; __device__ __forceinline__ void attn_run(LAS unsigned char* lds, const bf16* Kg, const bf16* Vg, int pitch, int t0, int t1,
;                                          const bf16x8 (&qr)[4], f32x16& o0, f32x16& o1, f32x16& o2, MaskF& mf, const int wv) {
;     ...
;     if (t0 >= t1) return;
;     const int lrow = tid >> 3, lch = tid & 7;
;     const unsigned kwoff = lrow * 144 + lch * 16;
;     const unsigned vwoff = ATT_V0 + lrow * 128 + (((lch >> 1) ^ (((lrow >> 1) & 1) << 1)) * 32) + (lch & 1) * 16;
;     const bf16* kp = Kg + (size_t)(64 * t0 + lrow) * pitch + lch * 8;
;     const bf16* vp = Vg + (size_t)(64 * t0 + lrow) * pitch + lch * 8;
;     const size_t tstride = (size_t)64 * pitch;
;     const v4u z4 = (v4u){0u, 0u, 0u, 0u};
;     v4u kreg0 = *(const v4u*)kp, kreg1 = z4, vreg0 = *(const v4u*)vp, vreg1 = z4;
;     if (t0 + 1 < t1) { kreg1 = *(const v4u*)(kp + tstride); vreg1 = *(const v4u*)(vp + tstride); }
; __device__ __forceinline__ void nsa_unit(const int wv, LAS unsigned char* lds, int b, int g, int c, const bf16* Y, const bf16* KCMP, const bf16* VCMP, const float* gates, bf16* OG) {
;     const int tid_ = fresh_tid(wv);
;     const int tid = tid_, lane = tid & 63, r32 = lane & 31, hi = lane >> 5, wid = tid >> 6;
;     const int hr = wid >> 1, tq = 32 * (wid & 1) + r32, tabs = 64 * c + tq, hh = 4 * g + hr;
;     LAS float* imph = (LAS float*)(lds + LDS_IMP);
;     LAS unsigned long long* selm = (LAS unsigned long long*)(lds + LDS_SEL);
;     for (int i = tid; i < 4 * 64 * 65; i += NTHREADS) imph[i] = 0.f;
;     __syncthreads();
;     const size_t row = (size_t)b * T + tabs;
;     bf16x8 qr[4]; load_q(Y + row * NSA_LDY + hh * 64, hi, qr);
;     const float* gp = gates + row * 48 + hh * 3; const float g0 = gp[0], g1 = gp[1], g2 = gp[2];
;     f32x16 acc0 = zero16(), acc1 = zero16();
;     LAS float* invl = (LAS float*)(lds + LDS_SEL + 512);
;     {
;         int ncnt = 4 * c + 3; if (ncnt > 255) ncnt = 255; const int nct = (ncnt + 63) >> 6;
;         CmpMask mf; mf.tabs = tabs; mf.hi = hi; mf.imp = imph + (hr * 64 + tq) * 65;
;         const bf16* Kg = KCMP + (size_t)(b * 4 + g) * 256 * 64; const bf16* Vg = VCMP + (size_t)(b * 4 + g) * 256 * 64;
;         f32x16 o0 = zero16(), o1 = zero16(), o2 = zero16();
;         attn_run<true>(lds, Kg, Vg, 64, 0, nct, qr, o0, o1, o2, mf, wv);
.LBB0_999:
	s_or_b64 exec, exec, s[4:5]
	v_lshrrev_b32_e32 v0, 1, v160
	v_and_b32_e32 v2, 31, v33
	v_and_b32_e32 v3, 32, v0
	v_or_b32_e32 v158, v3, v2
	v_readlane_b32 s0, v255, 12
	v_ashrrev_i32_e32 v8, 7, v160
	v_bfe_u32 v159, v33, 5, 1
	v_or_b32_e32 v152, s0, v158
	v_readlane_b32 s0, v254, 21
	v_ashrrev_i32_e32 v153, 31, v152
	v_lshlrev_b32_e32 v114, 4, v159
	v_add_u32_e32 v9, s0, v8
	v_readlane_b32 s0, v254, 9
	v_readlane_b32 s1, v254, 10
	v_lshlrev_b32_e32 v6, 6, v9
	v_ashrrev_i32_e32 v7, 31, v6
	v_lshl_add_u64 v[0:1], s[0:1], 0, v[152:153]
	v_readlane_b32 s0, v254, 27
	v_readlane_b32 s1, v254, 28
	s_waitcnt lgkmcnt(0)
	s_barrier
	v_mov_b64_e32 v[4:5], s[0:1]
	v_mad_u64_u32 v[4:5], s[0:1], v0, s84, v[4:5]
	v_mad_i32_i24 v5, v1, s84, v5
	v_lshl_add_u64 v[4:5], v[6:7], 1, v[4:5]
	v_readlane_b32 s0, v254, 35
	v_lshl_add_u64 v[4:5], v[4:5], 0, v[114:115]
	v_readlane_b32 s1, v254, 36
	global_load_dwordx4 v[116:119], v[4:5], off
	global_load_dwordx4 v[120:123], v[4:5], off offset:32
	global_load_dwordx4 v[124:127], v[4:5], off offset:64
	global_load_dwordx4 v[128:131], v[4:5], off offset:96
	v_add_co_u32_e32 v210, vcc, 0x1000, v4
	s_nop 1
	v_addc_co_u32_e32 v211, vcc, 0, v5, vcc
	v_mov_b64_e32 v[4:5], s[0:1]
	s_movk_i32 s4, 0xc0
	v_mad_u64_u32 v[4:5], s[0:1], v0, s4, v[4:5]
	v_lshl_add_u32 v0, v9, 1, v9
	v_mad_i32_i24 v5, v1, s4, v5
	v_ashrrev_i32_e32 v1, 31, v0
	v_lshl_add_u64 v[0:1], v[0:1], 2, v[4:5]
	global_load_dwordx3 v[182:184], v[0:1], off
	v_mov_b32_e32 v0, v115
	v_readlane_b32 s0, v254, 60
	v_mov_b32_e32 v0, v115
	v_readlane_b32 s1, v254, 61
	v_lshlrev_b32_e32 v153, 6, v8
	v_mov_b32_e32 v161, v115
	v_mov_b32_e32 v162, v115
	v_mov_b32_e32 v32, v115
	s_mov_b64 s[4:5], -1
	s_and_b64 vcc, exec, s[0:1]
	v_mbcnt_lo_u32_b32 v4, -1, 0
	v_mbcnt_hi_u32_b32 v4, -1, v4
	s_cbranch_vccz .LBB0_1034
	s_lshl_b32 s0, s19, 14
	v_readlane_b32 s1, v254, 39
	s_add_i32 s0, s0, s1
	s_lshl_b32 s4, s0, 1
	v_readlane_b32 s0, v254, 33
	v_add_u32_e32 v5, s83, v4
	s_add_u32 s0, s0, s4
	v_readlane_b32 s1, v254, 34
	s_addc_u32 s1, s1, 0
	v_readlane_b32 s5, v254, 31
	v_ashrrev_i32_e32 v0, 3, v5
	s_add_u32 s4, s5, s4
	v_readlane_b32 s5, v254, 32
	v_ashrrev_i32_e32 v1, 31, v0
	s_addc_u32 s5, s5, 0
	v_and_b32_e32 v6, 7, v4
	v_lshlrev_b64 v[8:9], 7, v[0:1]
	v_lshl_add_u64 v[10:11], s[4:5], 0, v[8:9]
	v_lshlrev_b32_e32 v114, 4, v6
	v_lshl_add_u64 v[154:155], v[10:11], 0, v[114:115]
	v_lshl_add_u64 v[8:9], s[0:1], 0, v[8:9]
	v_lshl_add_u64 v[156:157], v[8:9], 0, v[114:115]
	global_load_dwordx4 v[82:85], v[154:155], off
	global_load_dwordx4 v[86:89], v[156:157], off
	v_readlane_b32 s0, v254, 62
	v_readlane_b32 s1, v254, 63
	s_andn2_b64 vcc, exec, s[0:1]
	s_cbranch_vccnz .LBB0_1002
	v_add_co_u32_e32 v8, vcc, 0x2000, v154
	s_nop 1
	v_addc_co_u32_e32 v9, vcc, 0, v155, vcc
	v_add_co_u32_e32 v10, vcc, 0x2000, v156
	s_nop 1
	v_addc_co_u32_e32 v11, vcc, 0, v157, vcc
	global_load_dwordx4 v[90:93], v[8:9], off
	global_load_dwordx4 v[94:97], v[10:11], off
	s_branch .LBB0_1003

; #define LAS __attribute__((address_space(3)))
; template <bool HAS_POST, class MaskF>
; __device__ __forceinline__ void attn_run(LAS unsigned char* lds, const bf16* Kg, const bf16* Vg, int pitch, int t0, int t1,
;                                          const bf16x8 (&qr)[4], f32x16& o0, f32x16& o1, f32x16& o2, MaskF& mf, const int wv) {
;     ...
;     const unsigned kwoff = lrow * 144 + lch * 16;
;     const unsigned vwoff = ATT_V0 + lrow * 128 + (((lch >> 1) ^ (((lrow >> 1) & 1) << 1)) * 32) + (lch & 1) * 16;
;     const bf16* kp = Kg + (size_t)(64 * t0 + lrow) * pitch + lch * 8;
;     const bf16* vp = Vg + (size_t)(64 * t0 + lrow) * pitch + lch * 8;
;     const size_t tstride = (size_t)64 * pitch;
;     const v4u z4 = (v4u){0u, 0u, 0u, 0u};
;     v4u kreg0 = *(const v4u*)kp, kreg1 = z4, vreg0 = *(const v4u*)vp, vreg1 = z4;
;     if (t0 + 1 < t1) { kreg1 = *(const v4u*)(kp + tstride); vreg1 = *(const v4u*)(vp + tstride); }
;     *(LAS v4u*)(lds + kwoff) = kreg0; *(LAS v4u*)(lds + KBUF + kwoff) = kreg1;
;     *(LAS v4u*)(lds + vwoff) = vreg0; *(LAS v4u*)(lds + VBUF + vwoff) = vreg1;
;     __syncthreads();
.LBB0_1003:
	v_lshrrev_b32_e32 v6, 1, v6
	v_lshrrev_b32_e32 v7, 3, v4
	s_movk_i32 s0, 0x90
	v_bitop3_b32 v6, v6, v7, 2 bitop3:0x78
	v_lshlrev_b32_e32 v7, 4, v4
	v_mul_lo_u32 v1, v0, s0
	v_lshlrev_b32_e32 v0, 7, v0
	v_lshlrev_b32_e32 v6, 5, v6
	v_and_b32_e32 v7, 16, v7
	v_readlane_b32 s0, v253, 63
	v_or3_b32 v0, v0, v6, v7
	v_readlane_b32 s1, v254, 0
	v_add3_u32 v114, v1, v114, 0
	v_add_u32_e32 v163, 0, v0
	s_andn2_b64 vcc, exec, s[0:1]
	s_waitcnt vmcnt(1)
	ds_write_b128 v114, v[82:85]
	ds_write_b128 v114, v[90:93] offset:9216
	s_waitcnt vmcnt(0)
	ds_write_b128 v163, v[86:89] offset:36864
	ds_write_b128 v163, v[94:97] offset:45056
	s_waitcnt lgkmcnt(0)
	s_barrier
	global_load_dwordx4 v[212:215], v[210:211], off
	global_load_dwordx4 v[216:219], v[210:211], off offset:32
	global_load_dwordx4 v[220:223], v[210:211], off offset:64
	global_load_dwordx4 v[224:227], v[210:211], off offset:96
	s_cbranch_vccnz .LBB0_1005
	s_setprio 1

; __device__ __forceinline__ void moba_unit(const int wv, LAS unsigned char* lds, int b, int h, int qb, const bf16* Y, const float* kmean_l, bf16* OG) {
;     ...
;         for (int it = 0; it < 3; ++it) {
;             float best = -3.0e38f; int bi = -1;
; #pragma unroll
;             for (int n = 0; n < 16; ++n) { const bool ok = (n < qb) && !((mask >> n) & 1u); const float cand = ok ? ga[n] : -3.0e38f; if (cand > best) { best = cand; bi = n; } }
;             if (bi >= 0) mask |= (1u << bi);
;         }
.LBB0_1159:
	v_and_b32_e32 v18, 1, v17
	v_cmp_eq_u32_e64 s[6:7], 0, v18
	s_and_b64 s[6:7], s[4:5], s[6:7]
	v_and_b32_e32 v20, 2, v17
	v_cndmask_b32_e64 v18, v245, v1, s[6:7]
	v_cmp_nlt_f32_e64 s[6:7], s1, v18
	s_add_i32 s0, s0, -1
	s_nop 0
	v_cndmask_b32_e64 v18, v18, v245, s[6:7]
	v_cndmask_b32_e64 v19, 0, -1, s[6:7]
	v_cmp_eq_u32_e64 s[6:7], 0, v20
	s_and_b64 s[6:7], s[14:15], s[6:7]
	s_nop 0
	v_cndmask_b32_e64 v20, v245, v7, s[6:7]
	v_cmp_gt_f32_e64 s[6:7], v20, v18
	s_nop 1
	v_cndmask_b32_e64 v18, v18, v20, s[6:7]
	v_and_b32_e32 v20, 4, v17
	v_cndmask_b32_e64 v19, v19, 1, s[6:7]
	v_cmp_eq_u32_e64 s[6:7], 0, v20
	s_and_b64 s[6:7], s[16:17], s[6:7]
	s_nop 0
	v_cndmask_b32_e64 v20, v245, v11, s[6:7]
	v_cmp_gt_f32_e64 s[6:7], v20, v18
	s_nop 1
	v_cndmask_b32_e64 v18, v18, v20, s[6:7]
	v_and_b32_e32 v20, 8, v17
	v_cndmask_b32_e64 v19, v19, 2, s[6:7]
	v_cmp_eq_u32_e64 s[6:7], 0, v20
	s_and_b64 s[6:7], s[18:19], s[6:7]
	s_nop 0
	v_cndmask_b32_e64 v20, v245, v13, s[6:7]
	v_cmp_gt_f32_e64 s[6:7], v20, v18
	s_nop 1
	v_cndmask_b32_e64 v18, v18, v20, s[6:7]
	v_and_b32_e32 v20, 16, v17
	v_cndmask_b32_e64 v19, v19, 3, s[6:7]
	v_cmp_eq_u32_e64 s[6:7], 0, v20
	s_and_b64 s[6:7], s[20:21], s[6:7]
	s_nop 0
	v_cndmask_b32_e64 v20, v245, v14, s[6:7]
	v_cmp_gt_f32_e64 s[6:7], v20, v18
	s_nop 1
	v_cndmask_b32_e64 v18, v18, v20, s[6:7]
	v_and_b32_e32 v20, 32, v17
	v_cndmask_b32_e64 v19, v19, 4, s[6:7]
	v_cmp_eq_u32_e64 s[6:7], 0, v20
	s_and_b64 s[6:7], s[30:31], s[6:7]
	s_nop 0
	v_cndmask_b32_e64 v20, v245, v15, s[6:7]
	v_cmp_gt_f32_e64 s[6:7], v20, v18
	s_nop 1
	v_cndmask_b32_e64 v18, v18, v20, s[6:7]
	v_and_b32_e32 v20, 64, v17
	v_cndmask_b32_e64 v19, v19, 5, s[6:7]
	v_cmp_eq_u32_e64 s[6:7], 0, v20
	s_and_b64 s[6:7], s[38:39], s[6:7]
	s_nop 0
	v_cndmask_b32_e64 v20, v245, v16, s[6:7]
	v_cmp_gt_f32_e64 s[6:7], v20, v18
	s_nop 1
	v_cndmask_b32_e64 v18, v18, v20, s[6:7]
	v_and_b32_e32 v20, 0x80, v17
	v_cndmask_b32_e64 v19, v19, 6, s[6:7]
	v_cmp_eq_u32_e64 s[6:7], 0, v20
	s_and_b64 s[6:7], s[40:41], s[6:7]
	s_nop 0
	v_cndmask_b32_e64 v20, v245, v3, s[6:7]
	v_cmp_gt_f32_e64 s[6:7], v20, v18
	s_nop 1
	v_cndmask_b32_e64 v18, v18, v20, s[6:7]
	v_and_b32_e32 v20, 0x100, v17
	v_cndmask_b32_e64 v19, v19, 7, s[6:7]
	v_cmp_eq_u32_e64 s[6:7], 0, v20
	s_and_b64 s[6:7], s[42:43], s[6:7]
	s_nop 0
	v_cndmask_b32_e64 v20, v245, v6, s[6:7]
	v_cmp_gt_f32_e64 s[6:7], v20, v18
	s_nop 1
	v_cndmask_b32_e64 v18, v18, v20, s[6:7]
	v_and_b32_e32 v20, 0x200, v17
	v_cndmask_b32_e64 v19, v19, 8, s[6:7]
	v_cmp_eq_u32_e64 s[6:7], 0, v20
	s_and_b64 s[6:7], s[44:45], s[6:7]
	s_nop 0
	v_cndmask_b32_e64 v20, v245, v10, s[6:7]
	v_cmp_gt_f32_e64 s[6:7], v20, v18
	s_nop 1
	v_cndmask_b32_e64 v18, v18, v20, s[6:7]
	v_and_b32_e32 v20, 0x400, v17
	v_cndmask_b32_e64 v19, v19, 9, s[6:7]
	v_cmp_eq_u32_e64 s[6:7], 0, v20
	s_and_b64 s[6:7], s[46:47], s[6:7]
	s_nop 0
	v_cndmask_b32_e64 v20, v245, v8, s[6:7]
	v_cmp_gt_f32_e64 s[6:7], v20, v18
	s_nop 1
	v_cndmask_b32_e64 v18, v18, v20, s[6:7]
	v_and_b32_e32 v20, 0x800, v17
	v_cndmask_b32_e64 v19, v19, 10, s[6:7]
	v_cmp_eq_u32_e64 s[6:7], 0, v20
	s_and_b64 s[6:7], s[48:49], s[6:7]
	s_nop 0
	v_cndmask_b32_e64 v20, v245, v9, s[6:7]
	v_cmp_gt_f32_e64 s[6:7], v20, v18
	s_nop 1
	v_cndmask_b32_e64 v18, v18, v20, s[6:7]
	v_and_b32_e32 v20, 0x1000, v17
	v_cndmask_b32_e64 v19, v19, 11, s[6:7]
	v_cmp_eq_u32_e64 s[6:7], 0, v20
	s_and_b64 s[6:7], s[50:51], s[6:7]
	s_nop 0
	v_cndmask_b32_e64 v20, v245, v4, s[6:7]
	v_cmp_gt_f32_e64 s[6:7], v20, v18
	s_nop 1
	v_cndmask_b32_e64 v18, v18, v20, s[6:7]
	v_and_b32_e32 v20, 0x2000, v17
	v_cndmask_b32_e64 v19, v19, 12, s[6:7]
	v_cmp_eq_u32_e64 s[6:7], 0, v20
	s_and_b64 s[6:7], s[52:53], s[6:7]
	s_nop 0
	v_cndmask_b32_e64 v20, v245, v5, s[6:7]
	v_cmp_gt_f32_e64 s[6:7], v20, v18
	s_nop 1
	v_cndmask_b32_e64 v18, v18, v20, s[6:7]
	v_and_b32_e32 v20, 0x4000, v17
	v_cndmask_b32_e64 v19, v19, 13, s[6:7]
	v_cmp_eq_u32_e64 s[6:7], 0, v20
	s_and_b64 s[6:7], s[54:55], s[6:7]
	s_cmp_lg_u32 s0, 0
	v_cndmask_b32_e64 v20, v245, v2, s[6:7]
	v_cmp_gt_f32_e64 s[6:7], v20, v18
	s_nop 1
	v_cndmask_b32_e64 v18, v18, v20, s[6:7]
	v_cndmask_b32_e64 v19, v19, 14, s[6:7]
	v_cmp_ngt_f32_e64 s[6:7], s1, v18
	s_nop 1
	v_cndmask_b32_e64 v18, 15, v19, s[6:7]
	v_lshlrev_b32_e64 v19, v18, 1
	v_cmp_lt_i32_e64 s[6:7], -1, v18
	s_nop 1
	v_cndmask_b32_e64 v18, 0, v19, s[6:7]
	v_or_b32_e32 v17, v18, v17
	s_cbranch_scc1 .LBB0_1159
; #define LAS __attribute__((address_space(3)))
; template <bool HAS_POST, class MaskF>
; __device__ __forceinline__ void attn_run(LAS unsigned char* lds, const bf16* Kg, const bf16* Vg, int pitch, int t0, int t1,
;                                          const bf16x8 (&qr)[4], f32x16& o0, f32x16& o1, f32x16& o2, MaskF& mf, const int wv) {
;     ...
;     if (t0 >= t1) return;
;     const int lrow = tid >> 3, lch = tid & 7;
;     const unsigned kwoff = lrow * 144 + lch * 16;
;     const unsigned vwoff = ATT_V0 + lrow * 128 + (((lch >> 1) ^ (((lrow >> 1) & 1) << 1)) * 32) + (lch & 1) * 16;
;     const bf16* kp = Kg + (size_t)(64 * t0 + lrow) * pitch + lch * 8;
;     const bf16* vp = Vg + (size_t)(64 * t0 + lrow) * pitch + lch * 8;
;     const size_t tstride = (size_t)64 * pitch;
;     const v4u z4 = (v4u){0u, 0u, 0u, 0u};
;     v4u kreg0 = *(const v4u*)kp, kreg1 = z4, vreg0 = *(const v4u*)vp, vreg1 = z4;
;     if (t0 + 1 < t1) { kreg1 = *(const v4u*)(kp + tstride); vreg1 = *(const v4u*)(vp + tstride); }
;     *(LAS v4u*)(lds + kwoff) = kreg0; *(LAS v4u*)(lds + KBUF + kwoff) = kreg1;
;     *(LAS v4u*)(lds + vwoff) = vreg0; *(LAS v4u*)(lds + VBUF + vwoff) = vreg1;
;     __syncthreads();
; __device__ __forceinline__ void moba_unit(const int wv, LAS unsigned char* lds, int b, int h, int qb, const bf16* Y, const float* kmean_l, bf16* OG) {
;     ...
;         if (half == 0) selm[ql] = mask;
;     }
;     __syncthreads();
;     MobaMask mf; mf.qb = qb; mf.qrel = 32 * wid + r32; mf.hi = hi; mf.wq0 = 32 * wv; mf.sel = selm[32 * wid + r32];
;     const size_t row = rowblk + 32 * wid + r32;
;     bf16x8 qr[4]; load_q(Y + row * MOBA_LDY + h * 64, hi, qr);
;     f32x16 o0 = zero16(), o1 = zero16(), o2 = zero16();
;     const bf16* Kg = Y + (size_t)b * T * MOBA_LDY + 1024 + h * 64;
;     attn_run<false>(lds, Kg, Kg + 1024, MOBA_LDY, 0, 4 * qb + 4, qr, o0, o1, o2, mf, wv);
	s_and_saveexec_b64 s[4:5], vcc
	v_lshl_add_u32 v1, v0, 2, 0
	v_add_u32_e32 v1, 0x21400, v1
	ds_write_b32 v1, v17
	s_or_b64 exec, exec, s[4:5]
	v_and_b32_e32 v2, 0xffffffe0, v0
	s_movk_i32 s1, 0xffe0
	v_bfi_b32 v158, s1, v0, v12
	v_ashrrev_i32_e32 v3, 31, v2
	v_and_b32_e32 v1, 31, v12
	v_lshl_add_u32 v0, v158, 2, 0
	v_lshl_add_u64 v[112:113], s[10:11], 0, v[2:3]
	s_lshl_b32 s0, s12, 6
	v_add_u32_e32 v0, 0x21400, v0
	v_or_b32_e32 v112, v112, v1
	v_readlane_b32 s6, v254, 27
	s_and_b32 s0, s0, 0x3c0
	s_waitcnt lgkmcnt(0)
	s_barrier
	ds_read_b32 v159, v0
	v_lshlrev_b64 v[0:1], 13, v[112:113]
	v_readlane_b32 s7, v254, 28
	v_readlane_b32 s4, v254, 9
	v_bfe_u32 v48, v12, 5, 1
	v_lshl_add_u64 v[152:153], s[6:7], 0, v[0:1]
	v_readlane_b32 s5, v254, 10
	s_lshl_b32 s4, s0, 1
	v_lshlrev_b32_e32 v114, 4, v48
	v_lshl_add_u64 v[0:1], v[152:153], 0, s[4:5]
	v_lshl_add_u64 v[0:1], v[0:1], 0, v[114:115]
	global_load_dwordx4 v[80:83], v[0:1], off
	global_load_dwordx4 v[84:87], v[0:1], off offset:32
	global_load_dwordx4 v[88:91], v[0:1], off offset:64
	global_load_dwordx4 v[92:95], v[0:1], off offset:96
	v_add_co_u32_e32 v172, vcc, 0x1800, v0
	s_nop 1
	v_addc_co_u32_e32 v173, vcc, 0, v1, vcc
	v_mov_b32_e32 v16, v115
	v_mov_b32_e32 v0, v115
	v_mov_b32_e32 v32, v115
	s_lshl_b64 s[0:1], s[8:9], 25
	v_mbcnt_lo_u32_b32 v49, -1, 0
	v_mbcnt_hi_u32_b32 v49, -1, v49
	s_add_u32 s0, s6, s0
	v_bfe_u32 v3, v49, 1, 2
	v_lshrrev_b32_e32 v4, 3, v49
	v_add_u32_e32 v50, s83, v49
	v_bitop3_b32 v3, v3, v4, 2 bitop3:0x78
	s_addc_u32 s1, s7, s1
	v_writelane_b32 v254, s4, 9
	v_ashrrev_i32_e32 v2, 3, v50
	v_lshlrev_b32_e32 v7, 5, v3
	v_lshlrev_b32_e32 v3, 4, v49
	v_writelane_b32 v254, s5, 10
	s_add_u32 s0, s0, s4
	v_and_b32_e32 v1, 7, v49
	s_movk_i32 s4, 0x90
	v_and_b32_e32 v8, 16, v3
	v_ashrrev_i32_e32 v3, 31, v2
	s_addc_u32 s1, s1, 0
	v_mul_lo_u32 v6, v2, s4
	v_lshlrev_b32_e32 v114, 4, v1
	v_lshlrev_b32_e32 v1, 7, v2
	v_lshlrev_b64 v[2:3], 13, v[2:3]
	v_lshl_add_u64 v[2:3], s[0:1], 0, v[2:3]
	v_lshl_add_u64 v[2:3], v[2:3], 0, v[114:115]
	s_mov_b64 s[0:1], 0x800
	v_lshl_add_u64 v[154:155], v[2:3], 0, s[0:1]
	s_mov_b32 s0, 0x80000
	v_add_co_u32_e32 v4, vcc, s0, v2
	s_mov_b32 s0, 0x81000
	s_nop 0
	v_addc_co_u32_e32 v5, vcc, 0, v3, vcc
	global_load_dwordx4 v[96:99], v[2:3], off offset:2048
	global_load_dwordx4 v[100:103], v[154:155], off offset:2048
	v_add_co_u32_e32 v2, vcc, s0, v2
	global_load_dwordx4 v[104:107], v[4:5], off offset:2048
	s_nop 0
	v_addc_co_u32_e32 v3, vcc, 0, v3, vcc
	global_load_dwordx4 v[108:111], v[2:3], off
	v_readlane_b32 s0, v253, 63
	v_or3_b32 v1, v1, v7, v8
	v_readlane_b32 s1, v254, 0
	v_add3_u32 v160, v6, v114, 0
	v_add_u32_e32 v161, 0, v1
	s_andn2_b64 vcc, exec, s[0:1]
	s_waitcnt vmcnt(3)
	ds_write_b128 v160, v[96:99]
	s_waitcnt vmcnt(1)
	ds_write_b128 v160, v[104:107] offset:9216
	ds_write_b128 v161, v[100:103] offset:36864
	s_waitcnt vmcnt(0)
	ds_write_b128 v161, v[108:111] offset:45056
	s_waitcnt lgkmcnt(0)
	s_barrier
	global_load_dwordx4 v[198:201], v[172:173], off
	global_load_dwordx4 v[202:205], v[172:173], off offset:32
	global_load_dwordx4 v[206:209], v[172:173], off offset:64
	global_load_dwordx4 v[210:213], v[172:173], off offset:96
	s_cbranch_vccnz .LBB0_1164
	s_setprio 1
